# cumsum_seq in P1 tail rewritten: 64 (prompt) / 33 (sample) loads batched per lane instead of serialized load-wait-add; same f32 summation order
# speedup vs baseline: 1.0538x; 1.0295x over previous
.LBB0_362:
	s_and_b64 s[34:35], s[22:23], exec
	s_cselect_b32 s2, s20, s2
	s_ashr_i32 s38, s2, 3
	s_and_b32 s21, s2, 7
	s_and_b64 s[22:23], s[22:23], exec
	s_movk_i32 s2, 0x1000
	s_cselect_b32 s50, s2, 0x810
	s_add_i32 s2, s50, 63
	s_ashr_i32 s39, s38, 31
	v_readlane_b32 s52, v253, 0
	s_lshr_b32 s51, s2, 6
	s_lshl_b64 s[22:23], s[38:39], 9
	v_readlane_b32 s54, v253, 2
	v_readlane_b32 s53, v253, 1
	v_readlane_b32 s55, v253, 3
	v_readlane_b32 s56, v253, 4
	v_readlane_b32 s57, v253, 5
	v_readlane_b32 s58, v253, 6
	v_readlane_b32 s59, v253, 7
	s_add_u32 s22, s54, s22
	s_addc_u32 s23, s55, s23
	v_readlane_b32 s52, v253, 22
	s_lshl_b64 s[34:35], s[38:39], 16
	v_readlane_b32 s66, v253, 36
	v_readlane_b32 s67, v253, 37
	s_add_u32 s2, s66, s34
	s_addc_u32 s35, s67, s35
	s_lshl_b32 s40, s21, 2
	s_add_u32 s34, s2, s40
	s_addc_u32 s35, s35, 0
	s_lshl_b64 s[38:39], s[38:39], 17
	s_add_u32 s2, s47, s40
	s_addc_u32 s40, s48, 0
	v_mul_u32_u24_e32 v4, s51, v5
	s_add_u32 s38, s2, s38
	v_lshlrev_b32_e32 v2, 5, v4
	s_addc_u32 s39, s40, s39
	v_lshlrev_b32_e32 v17, 3, v4
	v_lshl_add_u64 v[6:7], s[38:39], 0, v[2:3]
	v_mov_b32_e32 v18, 0
	v_cndmask_b32_e64 v19, 0, 1, s[12:13]
	v_mov_b64_e32 v[8:9], v[6:7]
	v_mov_b32_e32 v2, v17
	v_mov_b32_e32 v20, v4
	s_mov_b32 s52, s51
	v_readlane_b32 s53, v253, 23
	v_readlane_b32 s54, v253, 24
	v_readlane_b32 s55, v253, 25
	v_readlane_b32 s56, v253, 26
	v_readlane_b32 s57, v253, 27
	v_readlane_b32 s58, v253, 28
	v_readlane_b32 s59, v253, 29
	v_readlane_b32 s60, v253, 30
	v_readlane_b32 s61, v253, 31
	v_readlane_b32 s62, v253, 32
	v_readlane_b32 s63, v253, 33
	v_readlane_b32 s64, v253, 34
	v_readlane_b32 s65, v253, 35
	s_cmp_gt_i32 s20, 31
	s_cbranch_scc1 .Lcs_sample
	global_load_dword v30, v[6:7], off
	global_load_dword v31, v[6:7], off offset:32
	global_load_dword v32, v[6:7], off offset:64
	global_load_dword v33, v[6:7], off offset:96
	global_load_dword v34, v[6:7], off offset:128
	global_load_dword v35, v[6:7], off offset:160
	global_load_dword v36, v[6:7], off offset:192
	global_load_dword v37, v[6:7], off offset:224
	global_load_dword v38, v[6:7], off offset:256
	global_load_dword v39, v[6:7], off offset:288
	global_load_dword v40, v[6:7], off offset:320
	global_load_dword v41, v[6:7], off offset:352
	global_load_dword v42, v[6:7], off offset:384
	global_load_dword v43, v[6:7], off offset:416
	global_load_dword v44, v[6:7], off offset:448
	global_load_dword v45, v[6:7], off offset:480
	global_load_dword v46, v[6:7], off offset:512
	global_load_dword v47, v[6:7], off offset:544
	global_load_dword v48, v[6:7], off offset:576
	global_load_dword v49, v[6:7], off offset:608
	global_load_dword v50, v[6:7], off offset:640
	global_load_dword v51, v[6:7], off offset:672
	global_load_dword v52, v[6:7], off offset:704
	global_load_dword v53, v[6:7], off offset:736
	global_load_dword v54, v[6:7], off offset:768
	global_load_dword v55, v[6:7], off offset:800
	global_load_dword v56, v[6:7], off offset:832
	global_load_dword v57, v[6:7], off offset:864
	global_load_dword v58, v[6:7], off offset:896
	global_load_dword v59, v[6:7], off offset:928
	global_load_dword v60, v[6:7], off offset:960
	global_load_dword v61, v[6:7], off offset:992
	global_load_dword v62, v[6:7], off offset:1024
	global_load_dword v63, v[6:7], off offset:1056
	global_load_dword v64, v[6:7], off offset:1088
	global_load_dword v65, v[6:7], off offset:1120
	global_load_dword v66, v[6:7], off offset:1152
	global_load_dword v67, v[6:7], off offset:1184
	global_load_dword v68, v[6:7], off offset:1216
	global_load_dword v69, v[6:7], off offset:1248
	global_load_dword v70, v[6:7], off offset:1280
	global_load_dword v71, v[6:7], off offset:1312
	global_load_dword v72, v[6:7], off offset:1344
	global_load_dword v73, v[6:7], off offset:1376
	global_load_dword v74, v[6:7], off offset:1408
	global_load_dword v75, v[6:7], off offset:1440
	global_load_dword v76, v[6:7], off offset:1472
	global_load_dword v77, v[6:7], off offset:1504
	global_load_dword v78, v[6:7], off offset:1536
	global_load_dword v79, v[6:7], off offset:1568
	global_load_dword v80, v[6:7], off offset:1600
	global_load_dword v81, v[6:7], off offset:1632
	global_load_dword v82, v[6:7], off offset:1664
	global_load_dword v83, v[6:7], off offset:1696
	global_load_dword v84, v[6:7], off offset:1728
	global_load_dword v85, v[6:7], off offset:1760
	global_load_dword v86, v[6:7], off offset:1792
	global_load_dword v87, v[6:7], off offset:1824
	global_load_dword v88, v[6:7], off offset:1856
	global_load_dword v89, v[6:7], off offset:1888
	global_load_dword v90, v[6:7], off offset:1920
	global_load_dword v91, v[6:7], off offset:1952
	global_load_dword v92, v[6:7], off offset:1984
	global_load_dword v93, v[6:7], off offset:2016
	s_waitcnt vmcnt(56)
	v_add_f32_e32 v18, v18, v30
	v_add_f32_e32 v18, v18, v31
	v_add_f32_e32 v18, v18, v32
	v_add_f32_e32 v18, v18, v33
	v_add_f32_e32 v18, v18, v34
	v_add_f32_e32 v18, v18, v35
	v_add_f32_e32 v18, v18, v36
	v_add_f32_e32 v18, v18, v37
	s_waitcnt vmcnt(48)
	v_add_f32_e32 v18, v18, v38
	v_add_f32_e32 v18, v18, v39
	v_add_f32_e32 v18, v18, v40
	v_add_f32_e32 v18, v18, v41
	v_add_f32_e32 v18, v18, v42
	v_add_f32_e32 v18, v18, v43
	v_add_f32_e32 v18, v18, v44
	v_add_f32_e32 v18, v18, v45
	s_waitcnt vmcnt(40)
	v_add_f32_e32 v18, v18, v46
	v_add_f32_e32 v18, v18, v47
	v_add_f32_e32 v18, v18, v48
	v_add_f32_e32 v18, v18, v49
	v_add_f32_e32 v18, v18, v50
	v_add_f32_e32 v18, v18, v51
	v_add_f32_e32 v18, v18, v52
	v_add_f32_e32 v18, v18, v53
	s_waitcnt vmcnt(32)
	v_add_f32_e32 v18, v18, v54
	v_add_f32_e32 v18, v18, v55
	v_add_f32_e32 v18, v18, v56
	v_add_f32_e32 v18, v18, v57
	v_add_f32_e32 v18, v18, v58
	v_add_f32_e32 v18, v18, v59
	v_add_f32_e32 v18, v18, v60
	v_add_f32_e32 v18, v18, v61
	s_waitcnt vmcnt(24)
	v_add_f32_e32 v18, v18, v62
	v_add_f32_e32 v18, v18, v63
	v_add_f32_e32 v18, v18, v64
	v_add_f32_e32 v18, v18, v65
	v_add_f32_e32 v18, v18, v66
	v_add_f32_e32 v18, v18, v67
	v_add_f32_e32 v18, v18, v68
	v_add_f32_e32 v18, v18, v69
	s_waitcnt vmcnt(16)
	v_add_f32_e32 v18, v18, v70
	v_add_f32_e32 v18, v18, v71
	v_add_f32_e32 v18, v18, v72
	v_add_f32_e32 v18, v18, v73
	v_add_f32_e32 v18, v18, v74
	v_add_f32_e32 v18, v18, v75
	v_add_f32_e32 v18, v18, v76
	v_add_f32_e32 v18, v18, v77
	s_waitcnt vmcnt(8)
	v_add_f32_e32 v18, v18, v78
	v_add_f32_e32 v18, v18, v79
	v_add_f32_e32 v18, v18, v80
	v_add_f32_e32 v18, v18, v81
	v_add_f32_e32 v18, v18, v82
	v_add_f32_e32 v18, v18, v83
	v_add_f32_e32 v18, v18, v84
	v_add_f32_e32 v18, v18, v85
	s_waitcnt vmcnt(0)
	v_add_f32_e32 v18, v18, v86
	v_add_f32_e32 v18, v18, v87
	v_add_f32_e32 v18, v18, v88
	v_add_f32_e32 v18, v18, v89
	v_add_f32_e32 v18, v18, v90
	v_add_f32_e32 v18, v18, v91
	v_add_f32_e32 v18, v18, v92
	v_add_f32_e32 v18, v18, v93
	s_branch .Lcs_scan
.Lcs_sample:
	s_lshl_b32 s2, s21, 2
	s_add_u32 s40, s22, s2
	s_addc_u32 s41, s23, 0
	s_add_u32 s40, s40, 0x9270000
	s_addc_u32 s41, s41, 0
	v_lshl_add_u64 v[22:23], v[2:3], 2, s[34:35]
	v_lshl_add_u64 v[24:25], v[2:3], 2, s[40:41]
	v_cmp_eq_u32_e32 vcc, 62, v5
	v_mov_b32_e32 v30, 0
	v_mov_b32_e32 v31, 0
	v_mov_b32_e32 v32, 0
	v_mov_b32_e32 v33, 0
	v_mov_b32_e32 v34, 0
	v_mov_b32_e32 v35, 0
	v_mov_b32_e32 v36, 0
	v_mov_b32_e32 v37, 0
	v_mov_b32_e32 v38, 0
	v_mov_b32_e32 v39, 0
	v_mov_b32_e32 v40, 0
	v_mov_b32_e32 v41, 0
	v_mov_b32_e32 v42, 0
	v_mov_b32_e32 v43, 0
	v_mov_b32_e32 v44, 0
	v_mov_b32_e32 v45, 0
	v_mov_b32_e32 v46, 0
	v_mov_b32_e32 v47, 0
	v_mov_b32_e32 v48, 0
	v_mov_b32_e32 v49, 0
	v_mov_b32_e32 v50, 0
	v_mov_b32_e32 v51, 0
	v_mov_b32_e32 v52, 0
	v_mov_b32_e32 v53, 0
	v_mov_b32_e32 v54, 0
	v_mov_b32_e32 v55, 0
	v_mov_b32_e32 v56, 0
	v_mov_b32_e32 v57, 0
	v_mov_b32_e32 v58, 0
	v_mov_b32_e32 v59, 0
	v_mov_b32_e32 v60, 0
	v_mov_b32_e32 v61, 0
	v_mov_b32_e32 v62, 0
	v_cndmask_b32_e32 v24, v22, v24, vcc
	v_cndmask_b32_e32 v25, v23, v25, vcc
	s_mov_b32 exec_lo, -1
	s_mov_b32 exec_hi, 0x7fffffff
	global_load_dword v30, v[22:23], off
	global_load_dword v31, v[22:23], off offset:32
	global_load_dword v32, v[24:25], off offset:64
	global_load_dword v33, v[24:25], off offset:96
	global_load_dword v34, v[24:25], off offset:128
	global_load_dword v35, v[24:25], off offset:160
	global_load_dword v36, v[24:25], off offset:192
	global_load_dword v37, v[24:25], off offset:224
	global_load_dword v38, v[24:25], off offset:256
	global_load_dword v39, v[24:25], off offset:288
	global_load_dword v40, v[24:25], off offset:320
	global_load_dword v41, v[24:25], off offset:352
	global_load_dword v42, v[24:25], off offset:384
	global_load_dword v43, v[24:25], off offset:416
	global_load_dword v44, v[24:25], off offset:448
	global_load_dword v45, v[24:25], off offset:480
	global_load_dword v46, v[24:25], off offset:512
	global_load_dword v47, v[24:25], off offset:544
	s_mov_b32 exec_hi, 0x3fffffff
	global_load_dword v48, v[22:23], off offset:576
	global_load_dword v49, v[22:23], off offset:608
	global_load_dword v50, v[22:23], off offset:640
	global_load_dword v51, v[22:23], off offset:672
	global_load_dword v52, v[22:23], off offset:704
	global_load_dword v53, v[22:23], off offset:736
	global_load_dword v54, v[22:23], off offset:768
	global_load_dword v55, v[22:23], off offset:800
	global_load_dword v56, v[22:23], off offset:832
	global_load_dword v57, v[22:23], off offset:864
	global_load_dword v58, v[22:23], off offset:896
	global_load_dword v59, v[22:23], off offset:928
	global_load_dword v60, v[22:23], off offset:960
	global_load_dword v61, v[22:23], off offset:992
	global_load_dword v62, v[22:23], off offset:1024
	s_mov_b64 exec, -1
	s_waitcnt vmcnt(0)
	v_add_f32_e32 v18, v18, v30
	v_add_f32_e32 v18, v18, v31
	v_add_f32_e32 v18, v18, v32
	v_add_f32_e32 v18, v18, v33
	v_add_f32_e32 v18, v18, v34
	v_add_f32_e32 v18, v18, v35
	v_add_f32_e32 v18, v18, v36
	v_add_f32_e32 v18, v18, v37
	v_add_f32_e32 v18, v18, v38
	v_add_f32_e32 v18, v18, v39
	v_add_f32_e32 v18, v18, v40
	v_add_f32_e32 v18, v18, v41
	v_add_f32_e32 v18, v18, v42
	v_add_f32_e32 v18, v18, v43
	v_add_f32_e32 v18, v18, v44
	v_add_f32_e32 v18, v18, v45
	v_add_f32_e32 v18, v18, v46
	v_add_f32_e32 v18, v18, v47
	v_add_f32_e32 v18, v18, v48
	v_add_f32_e32 v18, v18, v49
	v_add_f32_e32 v18, v18, v50
	v_add_f32_e32 v18, v18, v51
	v_add_f32_e32 v18, v18, v52
	v_add_f32_e32 v18, v18, v53
	v_add_f32_e32 v18, v18, v54
	v_add_f32_e32 v18, v18, v55
	v_add_f32_e32 v18, v18, v56
	v_add_f32_e32 v18, v18, v57
	v_add_f32_e32 v18, v18, v58
	v_add_f32_e32 v18, v18, v59
	v_add_f32_e32 v18, v18, v60
	v_add_f32_e32 v18, v18, v61
	v_add_f32_e32 v18, v18, v62
.Lcs_scan:
	ds_bpermute_b32 v2, v1, v18
	s_waitcnt lgkmcnt(0)
	v_add_f32_e32 v2, v18, v2
	v_cndmask_b32_e64 v2, v2, v18, s[0:1]
	ds_bpermute_b32 v8, v12, v2
	s_waitcnt lgkmcnt(0)
	v_add_f32_e32 v8, v2, v8
	v_cndmask_b32_e64 v2, v8, v2, s[14:15]
	ds_bpermute_b32 v8, v13, v2
	s_waitcnt lgkmcnt(0)
	v_add_f32_e32 v8, v2, v8
	v_cndmask_b32_e64 v2, v8, v2, s[4:5]
	ds_bpermute_b32 v8, v14, v2
	s_waitcnt lgkmcnt(0)
	v_add_f32_e32 v8, v2, v8
	v_cndmask_b32_e64 v2, v8, v2, s[6:7]
	ds_bpermute_b32 v8, v15, v2
	s_waitcnt lgkmcnt(0)
	v_add_f32_e32 v8, v2, v8
	v_cndmask_b32_e64 v10, v8, v2, s[8:9]
	ds_bpermute_b32 v11, v16, v10
	v_lshlrev_b32_e32 v2, 2, v4
	v_lshl_add_u64 v[8:9], s[36:37], 0, v[2:3]
	s_waitcnt lgkmcnt(0)
	v_add_f32_e32 v2, v10, v11
	v_cndmask_b32_e64 v2, v2, v10, s[10:11]
	v_sub_f32_e32 v18, v2, v18
	s_cmp_gt_i32 s20, 31
	s_cbranch_scc1 .Lcs_sample2
	v_add_f32_e32 v18, v18, v30
	v_mul_f32_e32 v30, 0x3fb8aa3b, v18
	global_store_dword v[8:9], v30, off
	v_add_f32_e32 v18, v18, v31
	v_mul_f32_e32 v31, 0x3fb8aa3b, v18
	global_store_dword v[8:9], v31, off offset:4
	v_add_f32_e32 v18, v18, v32
	v_mul_f32_e32 v32, 0x3fb8aa3b, v18
	global_store_dword v[8:9], v32, off offset:8
	v_add_f32_e32 v18, v18, v33
	v_mul_f32_e32 v33, 0x3fb8aa3b, v18
	global_store_dword v[8:9], v33, off offset:12
	v_add_f32_e32 v18, v18, v34
	v_mul_f32_e32 v34, 0x3fb8aa3b, v18
	global_store_dword v[8:9], v34, off offset:16
	v_add_f32_e32 v18, v18, v35
	v_mul_f32_e32 v35, 0x3fb8aa3b, v18
	global_store_dword v[8:9], v35, off offset:20
	v_add_f32_e32 v18, v18, v36
	v_mul_f32_e32 v36, 0x3fb8aa3b, v18
	global_store_dword v[8:9], v36, off offset:24
	v_add_f32_e32 v18, v18, v37
	v_mul_f32_e32 v37, 0x3fb8aa3b, v18
	global_store_dword v[8:9], v37, off offset:28
	v_add_f32_e32 v18, v18, v38
	v_mul_f32_e32 v38, 0x3fb8aa3b, v18
	global_store_dword v[8:9], v38, off offset:32
	v_add_f32_e32 v18, v18, v39
	v_mul_f32_e32 v39, 0x3fb8aa3b, v18
	global_store_dword v[8:9], v39, off offset:36
	v_add_f32_e32 v18, v18, v40
	v_mul_f32_e32 v40, 0x3fb8aa3b, v18
	global_store_dword v[8:9], v40, off offset:40
	v_add_f32_e32 v18, v18, v41
	v_mul_f32_e32 v41, 0x3fb8aa3b, v18
	global_store_dword v[8:9], v41, off offset:44
	v_add_f32_e32 v18, v18, v42
	v_mul_f32_e32 v42, 0x3fb8aa3b, v18
	global_store_dword v[8:9], v42, off offset:48
	v_add_f32_e32 v18, v18, v43
	v_mul_f32_e32 v43, 0x3fb8aa3b, v18
	global_store_dword v[8:9], v43, off offset:52
	v_add_f32_e32 v18, v18, v44
	v_mul_f32_e32 v44, 0x3fb8aa3b, v18
	global_store_dword v[8:9], v44, off offset:56
	v_add_f32_e32 v18, v18, v45
	v_mul_f32_e32 v45, 0x3fb8aa3b, v18
	global_store_dword v[8:9], v45, off offset:60
	v_add_f32_e32 v18, v18, v46
	v_mul_f32_e32 v46, 0x3fb8aa3b, v18
	global_store_dword v[8:9], v46, off offset:64
	v_add_f32_e32 v18, v18, v47
	v_mul_f32_e32 v47, 0x3fb8aa3b, v18
	global_store_dword v[8:9], v47, off offset:68
	v_add_f32_e32 v18, v18, v48
	v_mul_f32_e32 v48, 0x3fb8aa3b, v18
	global_store_dword v[8:9], v48, off offset:72
	v_add_f32_e32 v18, v18, v49
	v_mul_f32_e32 v49, 0x3fb8aa3b, v18
	global_store_dword v[8:9], v49, off offset:76
	v_add_f32_e32 v18, v18, v50
	v_mul_f32_e32 v50, 0x3fb8aa3b, v18
	global_store_dword v[8:9], v50, off offset:80
	v_add_f32_e32 v18, v18, v51
	v_mul_f32_e32 v51, 0x3fb8aa3b, v18
	global_store_dword v[8:9], v51, off offset:84
	v_add_f32_e32 v18, v18, v52
	v_mul_f32_e32 v52, 0x3fb8aa3b, v18
	global_store_dword v[8:9], v52, off offset:88
	v_add_f32_e32 v18, v18, v53
	v_mul_f32_e32 v53, 0x3fb8aa3b, v18
	global_store_dword v[8:9], v53, off offset:92
	v_add_f32_e32 v18, v18, v54
	v_mul_f32_e32 v54, 0x3fb8aa3b, v18
	global_store_dword v[8:9], v54, off offset:96
	v_add_f32_e32 v18, v18, v55
	v_mul_f32_e32 v55, 0x3fb8aa3b, v18
	global_store_dword v[8:9], v55, off offset:100
	v_add_f32_e32 v18, v18, v56
	v_mul_f32_e32 v56, 0x3fb8aa3b, v18
	global_store_dword v[8:9], v56, off offset:104
	v_add_f32_e32 v18, v18, v57
	v_mul_f32_e32 v57, 0x3fb8aa3b, v18
	global_store_dword v[8:9], v57, off offset:108
	v_add_f32_e32 v18, v18, v58
	v_mul_f32_e32 v58, 0x3fb8aa3b, v18
	global_store_dword v[8:9], v58, off offset:112
	v_add_f32_e32 v18, v18, v59
	v_mul_f32_e32 v59, 0x3fb8aa3b, v18
	global_store_dword v[8:9], v59, off offset:116
	v_add_f32_e32 v18, v18, v60
	v_mul_f32_e32 v60, 0x3fb8aa3b, v18
	global_store_dword v[8:9], v60, off offset:120
	v_add_f32_e32 v18, v18, v61
	v_mul_f32_e32 v61, 0x3fb8aa3b, v18
	global_store_dword v[8:9], v61, off offset:124
	v_add_f32_e32 v18, v18, v62
	v_mul_f32_e32 v62, 0x3fb8aa3b, v18
	global_store_dword v[8:9], v62, off offset:128
	v_add_f32_e32 v18, v18, v63
	v_mul_f32_e32 v63, 0x3fb8aa3b, v18
	global_store_dword v[8:9], v63, off offset:132
	v_add_f32_e32 v18, v18, v64
	v_mul_f32_e32 v64, 0x3fb8aa3b, v18
	global_store_dword v[8:9], v64, off offset:136
	v_add_f32_e32 v18, v18, v65
	v_mul_f32_e32 v65, 0x3fb8aa3b, v18
	global_store_dword v[8:9], v65, off offset:140
	v_add_f32_e32 v18, v18, v66
	v_mul_f32_e32 v66, 0x3fb8aa3b, v18
	global_store_dword v[8:9], v66, off offset:144
	v_add_f32_e32 v18, v18, v67
	v_mul_f32_e32 v67, 0x3fb8aa3b, v18
	global_store_dword v[8:9], v67, off offset:148
	v_add_f32_e32 v18, v18, v68
	v_mul_f32_e32 v68, 0x3fb8aa3b, v18
	global_store_dword v[8:9], v68, off offset:152
	v_add_f32_e32 v18, v18, v69
	v_mul_f32_e32 v69, 0x3fb8aa3b, v18
	global_store_dword v[8:9], v69, off offset:156
	v_add_f32_e32 v18, v18, v70
	v_mul_f32_e32 v70, 0x3fb8aa3b, v18
	global_store_dword v[8:9], v70, off offset:160
	v_add_f32_e32 v18, v18, v71
	v_mul_f32_e32 v71, 0x3fb8aa3b, v18
	global_store_dword v[8:9], v71, off offset:164
	v_add_f32_e32 v18, v18, v72
	v_mul_f32_e32 v72, 0x3fb8aa3b, v18
	global_store_dword v[8:9], v72, off offset:168
	v_add_f32_e32 v18, v18, v73
	v_mul_f32_e32 v73, 0x3fb8aa3b, v18
	global_store_dword v[8:9], v73, off offset:172
	v_add_f32_e32 v18, v18, v74
	v_mul_f32_e32 v74, 0x3fb8aa3b, v18
	global_store_dword v[8:9], v74, off offset:176
	v_add_f32_e32 v18, v18, v75
	v_mul_f32_e32 v75, 0x3fb8aa3b, v18
	global_store_dword v[8:9], v75, off offset:180
	v_add_f32_e32 v18, v18, v76
	v_mul_f32_e32 v76, 0x3fb8aa3b, v18
	global_store_dword v[8:9], v76, off offset:184
	v_add_f32_e32 v18, v18, v77
	v_mul_f32_e32 v77, 0x3fb8aa3b, v18
	global_store_dword v[8:9], v77, off offset:188
	v_add_f32_e32 v18, v18, v78
	v_mul_f32_e32 v78, 0x3fb8aa3b, v18
	global_store_dword v[8:9], v78, off offset:192
	v_add_f32_e32 v18, v18, v79
	v_mul_f32_e32 v79, 0x3fb8aa3b, v18
	global_store_dword v[8:9], v79, off offset:196
	v_add_f32_e32 v18, v18, v80
	v_mul_f32_e32 v80, 0x3fb8aa3b, v18
	global_store_dword v[8:9], v80, off offset:200
	v_add_f32_e32 v18, v18, v81
	v_mul_f32_e32 v81, 0x3fb8aa3b, v18
	global_store_dword v[8:9], v81, off offset:204
	v_add_f32_e32 v18, v18, v82
	v_mul_f32_e32 v82, 0x3fb8aa3b, v18
	global_store_dword v[8:9], v82, off offset:208
	v_add_f32_e32 v18, v18, v83
	v_mul_f32_e32 v83, 0x3fb8aa3b, v18
	global_store_dword v[8:9], v83, off offset:212
	v_add_f32_e32 v18, v18, v84
	v_mul_f32_e32 v84, 0x3fb8aa3b, v18
	global_store_dword v[8:9], v84, off offset:216
	v_add_f32_e32 v18, v18, v85
	v_mul_f32_e32 v85, 0x3fb8aa3b, v18
	global_store_dword v[8:9], v85, off offset:220
	v_add_f32_e32 v18, v18, v86
	v_mul_f32_e32 v86, 0x3fb8aa3b, v18
	global_store_dword v[8:9], v86, off offset:224
	v_add_f32_e32 v18, v18, v87
	v_mul_f32_e32 v87, 0x3fb8aa3b, v18
	global_store_dword v[8:9], v87, off offset:228
	v_add_f32_e32 v18, v18, v88
	v_mul_f32_e32 v88, 0x3fb8aa3b, v18
	global_store_dword v[8:9], v88, off offset:232
	v_add_f32_e32 v18, v18, v89
	v_mul_f32_e32 v89, 0x3fb8aa3b, v18
	global_store_dword v[8:9], v89, off offset:236
	v_add_f32_e32 v18, v18, v90
	v_mul_f32_e32 v90, 0x3fb8aa3b, v18
	global_store_dword v[8:9], v90, off offset:240
	v_add_f32_e32 v18, v18, v91
	v_mul_f32_e32 v91, 0x3fb8aa3b, v18
	global_store_dword v[8:9], v91, off offset:244
	v_add_f32_e32 v18, v18, v92
	v_mul_f32_e32 v92, 0x3fb8aa3b, v18
	global_store_dword v[8:9], v92, off offset:248
	v_add_f32_e32 v18, v18, v93
	v_mul_f32_e32 v93, 0x3fb8aa3b, v18
	global_store_dword v[8:9], v93, off offset:252
	s_branch .LBB0_357
.Lcs_sample2:
	v_add_f32_e32 v18, v18, v30
	v_mul_f32_e32 v30, 0x3fb8aa3b, v18
	v_add_f32_e32 v18, v18, v31
	v_mul_f32_e32 v31, 0x3fb8aa3b, v18
	v_add_f32_e32 v18, v18, v32
	v_mul_f32_e32 v32, 0x3fb8aa3b, v18
	v_add_f32_e32 v18, v18, v33
	v_mul_f32_e32 v33, 0x3fb8aa3b, v18
	v_add_f32_e32 v18, v18, v34
	v_mul_f32_e32 v34, 0x3fb8aa3b, v18
	v_add_f32_e32 v18, v18, v35
	v_mul_f32_e32 v35, 0x3fb8aa3b, v18
	v_add_f32_e32 v18, v18, v36
	v_mul_f32_e32 v36, 0x3fb8aa3b, v18
	v_add_f32_e32 v18, v18, v37
	v_mul_f32_e32 v37, 0x3fb8aa3b, v18
	v_add_f32_e32 v18, v18, v38
	v_mul_f32_e32 v38, 0x3fb8aa3b, v18
	v_add_f32_e32 v18, v18, v39
	v_mul_f32_e32 v39, 0x3fb8aa3b, v18
	v_add_f32_e32 v18, v18, v40
	v_mul_f32_e32 v40, 0x3fb8aa3b, v18
	v_add_f32_e32 v18, v18, v41
	v_mul_f32_e32 v41, 0x3fb8aa3b, v18
	v_add_f32_e32 v18, v18, v42
	v_mul_f32_e32 v42, 0x3fb8aa3b, v18
	v_add_f32_e32 v18, v18, v43
	v_mul_f32_e32 v43, 0x3fb8aa3b, v18
	v_add_f32_e32 v18, v18, v44
	v_mul_f32_e32 v44, 0x3fb8aa3b, v18
	v_add_f32_e32 v18, v18, v45
	v_mul_f32_e32 v45, 0x3fb8aa3b, v18
	v_add_f32_e32 v18, v18, v46
	v_mul_f32_e32 v46, 0x3fb8aa3b, v18
	v_add_f32_e32 v18, v18, v47
	v_mul_f32_e32 v47, 0x3fb8aa3b, v18
	v_add_f32_e32 v18, v18, v48
	v_mul_f32_e32 v48, 0x3fb8aa3b, v18
	v_add_f32_e32 v18, v18, v49
	v_mul_f32_e32 v49, 0x3fb8aa3b, v18
	v_add_f32_e32 v18, v18, v50
	v_mul_f32_e32 v50, 0x3fb8aa3b, v18
	v_add_f32_e32 v18, v18, v51
	v_mul_f32_e32 v51, 0x3fb8aa3b, v18
	v_add_f32_e32 v18, v18, v52
	v_mul_f32_e32 v52, 0x3fb8aa3b, v18
	v_add_f32_e32 v18, v18, v53
	v_mul_f32_e32 v53, 0x3fb8aa3b, v18
	v_add_f32_e32 v18, v18, v54
	v_mul_f32_e32 v54, 0x3fb8aa3b, v18
	v_add_f32_e32 v18, v18, v55
	v_mul_f32_e32 v55, 0x3fb8aa3b, v18
	v_add_f32_e32 v18, v18, v56
	v_mul_f32_e32 v56, 0x3fb8aa3b, v18
	v_add_f32_e32 v18, v18, v57
	v_mul_f32_e32 v57, 0x3fb8aa3b, v18
	v_add_f32_e32 v18, v18, v58
	v_mul_f32_e32 v58, 0x3fb8aa3b, v18
	v_add_f32_e32 v18, v18, v59
	v_mul_f32_e32 v59, 0x3fb8aa3b, v18
	v_add_f32_e32 v18, v18, v60
	v_mul_f32_e32 v60, 0x3fb8aa3b, v18
	v_add_f32_e32 v18, v18, v61
	v_mul_f32_e32 v61, 0x3fb8aa3b, v18
	v_add_f32_e32 v18, v18, v62
	v_mul_f32_e32 v62, 0x3fb8aa3b, v18
	s_mov_b32 exec_lo, -1
	s_mov_b32 exec_hi, 0x7fffffff
	global_store_dword v[8:9], v30, off
	global_store_dword v[8:9], v31, off offset:4
	global_store_dword v[8:9], v32, off offset:8
	global_store_dword v[8:9], v33, off offset:12
	global_store_dword v[8:9], v34, off offset:16
	global_store_dword v[8:9], v35, off offset:20
	global_store_dword v[8:9], v36, off offset:24
	global_store_dword v[8:9], v37, off offset:28
	global_store_dword v[8:9], v38, off offset:32
	global_store_dword v[8:9], v39, off offset:36
	global_store_dword v[8:9], v40, off offset:40
	global_store_dword v[8:9], v41, off offset:44
	global_store_dword v[8:9], v42, off offset:48
	global_store_dword v[8:9], v43, off offset:52
	global_store_dword v[8:9], v44, off offset:56
	global_store_dword v[8:9], v45, off offset:60
	global_store_dword v[8:9], v46, off offset:64
	global_store_dword v[8:9], v47, off offset:68
	s_mov_b32 exec_hi, 0x3fffffff
	global_store_dword v[8:9], v48, off offset:72
	global_store_dword v[8:9], v49, off offset:76
	global_store_dword v[8:9], v50, off offset:80
	global_store_dword v[8:9], v51, off offset:84
	global_store_dword v[8:9], v52, off offset:88
	global_store_dword v[8:9], v53, off offset:92
	global_store_dword v[8:9], v54, off offset:96
	global_store_dword v[8:9], v55, off offset:100
	global_store_dword v[8:9], v56, off offset:104
	global_store_dword v[8:9], v57, off offset:108
	global_store_dword v[8:9], v58, off offset:112
	global_store_dword v[8:9], v59, off offset:116
	global_store_dword v[8:9], v60, off offset:120
	global_store_dword v[8:9], v61, off offset:124
	global_store_dword v[8:9], v62, off offset:128
	s_mov_b64 exec, -1
	s_branch .LBB0_357
